# nt (non-temporal) cache policy on the norm phases' once-read f32 residual row loads, on top of v24
# speedup vs baseline: 1.0070x; 1.0070x over previous
; __device__ __forceinline__ int opaque_tid() { int t = threadIdx.x; asm volatile("" : "+v"(t)); return t; }
; __device__ __forceinline__ void norm_phase(const float* xL, const float* xC, const float* gain, const float* modl  , int ishift, bf16_t* H, int nrows,
;                                            const float* part, int nsplit, const float* pgate  , float pscale, float* xCw) {
;     const int tid_ = opaque_tid(); const int lane = tid_ & 63, wave = __builtin_amdgcn_readfirstlane(tid_ >> 6);
;     const int gw = blockIdx.x * NWAVES + wave, NGW = gridDim.x * NWAVES;
;     f32x4 gn[4];
; #pragma unroll
;     for (int j = 0; j < 4; ++j) gn[j] = *(const f32x4*)(gain + 4 * lane + 256 * j);
;     const int nplain = (nsplit > 0 && nrows > RL) ? RL : nrows;
;     {
;         int row = gw; f32x4 v[4], vn[4];
;         if (row < nplain) { const float* xr = row < RL ? xL + (size_t)row * DM : xC + (size_t)(row - RL) * DM;
; #pragma unroll
;             for (int j = 0; j < 4; ++j) v[j] = *(const f32x4*)(xr + 4 * lane + 256 * j); }
;         for (; row < nplain; row += NGW) {
;             const int rn = row + NGW;
;             if (rn < nplain) { const float* xr = rn < RL ? xL + (size_t)rn * DM : xC + (size_t)(rn - RL) * DM;
; #pragma unroll
;                 for (int j = 0; j < 4; ++j) vn[j] = *(const f32x4*)(xr + 4 * lane + 256 * j); }
.LBB0_106:
	v_writelane_b32 v252, s48, 18
	s_mul_i32 s1, s21, 0x2d000
	s_mul_hi_u32 s0, s21, 0x2d000
	v_writelane_b32 v252, s49, 19
	v_writelane_b32 v252, s50, 20
	v_writelane_b32 v252, s51, 21
	v_writelane_b32 v252, s52, 22
	v_writelane_b32 v252, s53, 23
	v_writelane_b32 v252, s54, 24
	v_writelane_b32 v252, s55, 25
	v_writelane_b32 v252, s56, 26
	v_writelane_b32 v252, s57, 27
	v_writelane_b32 v252, s58, 28
	v_writelane_b32 v252, s59, 29
	v_writelane_b32 v252, s60, 30
	v_writelane_b32 v252, s61, 31
	v_writelane_b32 v252, s62, 32
	v_writelane_b32 v252, s63, 33
	v_writelane_b32 v255, s21, 20
	v_readlane_b32 s5, v252, 55
	s_add_u32 s6, s5, s1
	v_readlane_b32 s1, v252, 56
	s_addc_u32 s7, s1, s0
	v_writelane_b32 v255, s6, 21
	s_lshl_b32 s22, s21, 10
	v_readlane_b32 s68, v252, 34
	v_mov_b32_e32 v16, v192
	v_writelane_b32 v255, s7, 22
	s_lshl_b64 s[6:7], s[22:23], 2
	v_readlane_b32 s80, v252, 46
	v_readlane_b32 s81, v252, 47
	v_lshlrev_b32_e32 v0, 2, v16
	s_add_u32 s0, s80, s6
	v_and_b32_e32 v0, 0xfc, v0
	v_readlane_b32 s38, v255, 20
	v_writelane_b32 v255, s6, 23
	s_addc_u32 s1, s81, s7
	v_lshlrev_b32_e32 v194, 2, v0
	global_load_dwordx4 v[0:3], v194, s[0:1]
	global_load_dwordx4 v[4:7], v194, s[0:1] offset:1024
	global_load_dwordx4 v[8:11], v194, s[0:1] offset:2048
	global_load_dwordx4 v[12:15], v194, s[0:1] offset:3072
	v_readfirstlane_b32 s0, v16
	s_ashr_i32 s10, s0, 6
	v_readlane_b32 s0, v252, 50
	s_add_i32 s8, s10, s0
	s_cmp_lg_u32 s38, 0
	s_cselect_b64 s[0:1], -1, 0
	v_writelane_b32 v255, s7, 24
	s_and_b64 s[6:7], s[0:1], exec
	v_readlane_b32 s20, v252, 53
	s_mov_b32 s5, 0x8000
	v_readlane_b32 s69, v252, 35
	v_readlane_b32 s21, v252, 54
	s_cselect_b32 s5, s5, 0x8400
	v_readlane_b32 s50, v252, 59
	v_readlane_b32 s52, v252, 61
	v_readlane_b32 s54, v252, 63
	v_readlane_b32 s60, v253, 1
	s_cselect_b32 s7, s21, s69
	s_cselect_b32 s6, s20, s68
	s_cmp_ge_i32 s8, s5
	v_and_b32_e32 v50, 63, v16
	v_readlane_b32 s51, v252, 60
	v_readlane_b32 s53, v252, 62
	v_readlane_b32 s55, v253, 0
	v_readlane_b32 s61, v253, 2
	s_movk_i32 s22, 0x16c
	s_mov_b32 s49, 0x10000
	s_mov_b32 s62, 0x20000
	s_mov_b32 s63, 0x30000
	v_readlane_b32 s70, v252, 36
	v_readlane_b32 s71, v252, 37
	v_readlane_b32 s72, v252, 38
	v_readlane_b32 s73, v252, 39
	v_readlane_b32 s74, v252, 40
	v_readlane_b32 s75, v252, 41
	v_readlane_b32 s76, v252, 42
	v_readlane_b32 s77, v252, 43
	v_readlane_b32 s78, v252, 44
	v_readlane_b32 s79, v252, 45
	v_readlane_b32 s82, v252, 48
	v_readlane_b32 s83, v252, 49
	s_cbranch_scc1 .LBB0_112
	v_readlane_b32 s68, v252, 34
	v_readlane_b32 s14, v252, 16
	s_and_b64 s[12:13], s[0:1], exec
	v_readlane_b32 s72, v252, 38
	v_readlane_b32 s73, v252, 39
	v_readlane_b32 s15, v252, 17
	s_cselect_b32 s12, s15, s73
	s_cselect_b32 s13, s14, s72
	s_add_i32 s11, s8, 0xffff8000
	s_ashr_i32 s9, s8, 31
	s_cmp_lt_i32 s8, 0x8000
	s_cselect_b32 s15, s9, 0
	s_cselect_b32 s14, s8, s11
	s_cselect_b32 s11, s7, s12
	s_cselect_b32 s16, s6, s13
	s_lshl_b64 s[14:15], s[14:15], 12
	s_add_u32 s14, s16, s14
	s_addc_u32 s15, s11, s15
	global_load_dwordx4 v[16:19], v194, s[14:15] offset:3072 nt
	global_load_dwordx4 v[36:39], v194, s[14:15] offset:2048 nt
	global_load_dwordx4 v[44:47], v194, s[14:15] nt
	global_load_dwordx4 v[40:43], v194, s[14:15] offset:1024 nt
	s_lshl_b64 s[14:15], s[8:9], 11
	s_add_u32 s14, s86, s14
	v_readlane_b32 s9, v255, 4
	v_lshlrev_b32_e32 v48, 3, v50
	v_mov_b32_e32 v49, v195
	s_addc_u32 s15, s87, s15
	s_add_i32 s9, s9, s10
	v_readlane_b32 s38, v255, 21
	s_mov_b32 s16, s8
	v_lshl_add_u64 v[48:49], s[14:15], 0, v[48:49]
	s_ashr_i32 s14, s9, 31
	s_movk_i32 s20, 0x1000
	v_readlane_b32 s39, v255, 22
	v_readlane_b32 s69, v252, 35
	v_readlane_b32 s70, v252, 36
	v_readlane_b32 s71, v252, 37
	v_readlane_b32 s74, v252, 40
	v_readlane_b32 s75, v252, 41
	v_readlane_b32 s76, v252, 42
	v_readlane_b32 s77, v252, 43
	v_readlane_b32 s78, v252, 44
	v_readlane_b32 s79, v252, 45
	v_readlane_b32 s80, v252, 46
	v_readlane_b32 s81, v252, 47
	v_readlane_b32 s82, v252, 48
	v_readlane_b32 s83, v252, 49
	s_waitcnt vmcnt(3)
	v_mov_b32_e32 v51, v16
	v_mov_b32_e32 v53, v17
	v_mov_b32_e32 v52, v18
	v_mov_b32_e32 v54, v19
	s_branch .LBB0_109

; __device__ __forceinline__ void norm_phase(const float* xL, const float* xC, const float* gain, const float* modl  , int ishift, bf16_t* H, int nrows,
;                                            const float* part, int nsplit, const float* pgate  , float pscale, float* xCw) {
;     ...
;         for (; row < nplain; row += NGW) {
;             const int rn = row + NGW;
;             if (rn < nplain) { const float* xr = rn < RL ? xL + (size_t)rn * DM : xC + (size_t)(rn - RL) * DM;
; #pragma unroll
;                 for (int j = 0; j < 4; ++j) vn[j] = *(const f32x4*)(xr + 4 * lane + 256 * j); }
.LBB0_109:
	s_add_i32 s15, s16, s88
	s_cmp_ge_i32 s15, s5
	s_cselect_b64 s[10:11], -1, 0
	s_and_b64 vcc, exec, s[10:11]
	s_cbranch_vccnz .LBB0_108
	s_add_i32 s17, s15, 0xffff8000
	s_cmp_lt_i32 s15, 0x8000
	s_cselect_b32 s19, s14, 0
	s_cselect_b32 s18, s9, s17
	s_cselect_b32 s17, s7, s12
	s_cselect_b32 s34, s6, s13
	s_lshl_b64 s[18:19], s[18:19], 12
	s_add_u32 s18, s34, s18
	s_addc_u32 s19, s17, s19
	global_load_dwordx4 v[32:35], v194, s[18:19] nt
	global_load_dwordx4 v[28:31], v194, s[18:19] offset:1024 nt
	global_load_dwordx4 v[24:27], v194, s[18:19] offset:2048 nt
	global_load_dwordx4 v[20:23], v194, s[18:19] offset:3072 nt
	s_branch .LBB0_108

; __device__ __forceinline__ int opaque_tid() { int t = threadIdx.x; asm volatile("" : "+v"(t)); return t; }
; __device__ __forceinline__ void norm_phase(const float* xL, const float* xC, const float* gain, const float* modl  , int ishift, bf16_t* H, int nrows,
;                                            const float* part, int nsplit, const float* pgate  , float pscale, float* xCw) {
;     const int tid_ = opaque_tid(); const int lane = tid_ & 63, wave = __builtin_amdgcn_readfirstlane(tid_ >> 6);
;     const int gw = blockIdx.x * NWAVES + wave, NGW = gridDim.x * NWAVES;
;     f32x4 gn[4];
; #pragma unroll
;     for (int j = 0; j < 4; ++j) gn[j] = *(const f32x4*)(gain + 4 * lane + 256 * j);
;     const int nplain = (nsplit > 0 && nrows > RL) ? RL : nrows;
;     {
;         int row = gw; f32x4 v[4], vn[4];
;         if (row < nplain) { const float* xr = row < RL ? xL + (size_t)row * DM : xC + (size_t)(row - RL) * DM;
; #pragma unroll
;             for (int j = 0; j < 4; ++j) v[j] = *(const f32x4*)(xr + 4 * lane + 256 * j); }
;         for (; row < nplain; row += NGW) {
;             const int rn = row + NGW;
;             if (rn < nplain) { const float* xr = rn < RL ? xL + (size_t)rn * DM : xC + (size_t)(rn - RL) * DM;
; #pragma unroll
;                 for (int j = 0; j < 4; ++j) vn[j] = *(const f32x4*)(xr + 4 * lane + 256 * j); }
.LBB0_327:
	s_or_b64 exec, exec, s[0:1]
	v_readlane_b32 s48, v252, 0
	v_readlane_b32 s50, v252, 2
	v_readlane_b32 s51, v252, 3
	v_mov_b32_e32 v16, v192
	s_waitcnt lgkmcnt(0)
	s_barrier
	s_mov_b64 s[6:7], s[50:51]
	v_readlane_b32 s0, v255, 23
	v_readlane_b32 s1, v255, 24
	v_lshlrev_b32_e32 v0, 2, v16
	s_add_u32 s0, s6, s0
	v_and_b32_e32 v0, 0xfc, v0
	s_addc_u32 s1, s7, s1
	v_lshlrev_b32_e32 v194, 2, v0
	global_load_dwordx4 v[0:3], v194, s[0:1]
	global_load_dwordx4 v[4:7], v194, s[0:1] offset:1024
	global_load_dwordx4 v[8:11], v194, s[0:1] offset:2048
	global_load_dwordx4 v[12:15], v194, s[0:1] offset:3072
	v_readfirstlane_b32 s0, v16
	v_readlane_b32 s60, v252, 12
	v_readlane_b32 s61, v252, 13
	s_ashr_i32 s0, s0, 6
	v_readlane_b32 s1, v252, 50
	v_readlane_b32 s63, v252, 15
	s_add_i32 s6, s0, s1
	v_readlane_b32 s60, v254, 21
	s_cmpk_gt_i32 s6, 0x7fff
	v_and_b32_e32 v72, 63, v16
	v_readlane_b32 s77, v255, 18
	v_readlane_b32 s61, v254, 22
	s_movk_i32 s63, 0x60
	v_readlane_b32 s49, v252, 1
	v_readlane_b32 s52, v252, 4
	v_readlane_b32 s53, v252, 5
	v_readlane_b32 s54, v252, 6
	v_readlane_b32 s55, v252, 7
	v_readlane_b32 s56, v252, 8
	v_readlane_b32 s57, v252, 9
	v_readlane_b32 s58, v252, 10
	v_readlane_b32 s59, v252, 11
	v_readlane_b32 s62, v252, 14
	s_cbranch_scc1 .LBB0_332
	s_ashr_i32 s7, s6, 31
	s_lshl_b64 s[8:9], s[6:7], 12
	v_readlane_b32 s10, v252, 53
	v_readlane_b32 s11, v252, 54
	s_add_u32 s8, s10, s8
	s_addc_u32 s9, s11, s9
	global_load_dwordx4 v[44:47], v194, s[8:9] nt
	global_load_dwordx4 v[40:43], v194, s[8:9] offset:1024 nt
	global_load_dwordx4 v[36:39], v194, s[8:9] offset:2048 nt
	global_load_dwordx4 v[16:19], v194, s[8:9] offset:3072 nt
	v_readlane_b32 s8, v255, 21
	v_readlane_b32 s9, v255, 22
	s_add_u32 s5, s8, 0x3000
	v_readlane_b32 s1, v255, 4
	s_addc_u32 s8, s9, 0
	s_add_i32 s0, s1, s0
	s_ashr_i32 s1, s0, 31
	s_lshl_b64 s[10:11], s[6:7], 11
	s_lshl_b64 s[0:1], s[0:1], 12
	v_lshl_or_b32 v64, v72, 3, s10
	v_mov_b32_e32 v65, s11
	v_lshl_or_b32 v66, v72, 4, s0
	v_mov_b32_e32 v67, s1
	s_mov_b32 s9, s6
	s_mov_b64 s[12:13], 0x1000
	s_waitcnt vmcnt(0)
	v_mov_b32_e32 v68, v16
	v_mov_b32_e32 v70, v17
	v_mov_b32_e32 v69, v18
	v_mov_b32_e32 v71, v19
	s_branch .LBB0_330

; __device__ __forceinline__ void norm_phase(const float* xL, const float* xC, const float* gain, const float* modl  , int ishift, bf16_t* H, int nrows,
;                                            const float* part, int nsplit, const float* pgate  , float pscale, float* xCw) {
;     ...
;         for (; row < nplain; row += NGW) {
;             const int rn = row + NGW;
;             if (rn < nplain) { const float* xr = rn < RL ? xL + (size_t)rn * DM : xC + (size_t)(rn - RL) * DM;
; #pragma unroll
;                 for (int j = 0; j < 4; ++j) vn[j] = *(const f32x4*)(xr + 4 * lane + 256 * j); }
.LBB0_330:
	s_add_i32 s7, s9, s88
	s_cmpk_gt_i32 s7, 0x7fff
	s_cselect_b64 s[0:1], -1, 0
	s_and_b64 vcc, exec, s[0:1]
	s_cbranch_vccnz .LBB0_329
	v_lshl_add_u64 v[20:21], s[96:97], 0, v[66:67]
	v_add_co_u32_e32 v20, vcc, 0xa000000, v20
	s_nop 1
	v_addc_co_u32_e32 v21, vcc, 0, v21, vcc
	global_load_dwordx4 v[32:35], v[20:21], off nt
	global_load_dwordx4 v[28:31], v[20:21], off offset:1024 nt
	global_load_dwordx4 v[24:27], v[20:21], off offset:2048 nt
	s_nop 0
	global_load_dwordx4 v[20:23], v[20:21], off offset:3072 nt
	s_branch .LBB0_329

; __device__ __forceinline__ int opaque_tid() { int t = threadIdx.x; asm volatile("" : "+v"(t)); return t; }
; __device__ __forceinline__ void norm_phase(const float* xL, const float* xC, const float* gain, const float* modl  , int ishift, bf16_t* H, int nrows,
;                                            const float* part, int nsplit, const float* pgate  , float pscale, float* xCw) {
;     const int tid_ = opaque_tid(); const int lane = tid_ & 63, wave = __builtin_amdgcn_readfirstlane(tid_ >> 6);
;     const int gw = blockIdx.x * NWAVES + wave, NGW = gridDim.x * NWAVES;
;     f32x4 gn[4];
; #pragma unroll
;     for (int j = 0; j < 4; ++j) gn[j] = *(const f32x4*)(gain + 4 * lane + 256 * j);
;     const int nplain = (nsplit > 0 && nrows > RL) ? RL : nrows;
;     {
;         int row = gw; f32x4 v[4], vn[4];
;         if (row < nplain) { const float* xr = row < RL ? xL + (size_t)row * DM : xC + (size_t)(row - RL) * DM;
; #pragma unroll
;             for (int j = 0; j < 4; ++j) v[j] = *(const f32x4*)(xr + 4 * lane + 256 * j); }
;         for (; row < nplain; row += NGW) {
;             const int rn = row + NGW;
;             if (rn < nplain) { const float* xr = rn < RL ? xL + (size_t)rn * DM : xC + (size_t)(rn - RL) * DM;
; #pragma unroll
;                 for (int j = 0; j < 4; ++j) vn[j] = *(const f32x4*)(xr + 4 * lane + 256 * j); }
.LBB0_997:
	s_or_b64 exec, exec, s[0:1]
	v_mov_b32_e32 v16, v192
	s_waitcnt lgkmcnt(0)
	s_barrier
	v_readlane_b32 s0, v255, 23
	v_readlane_b32 s1, v255, 24
	v_lshlrev_b32_e32 v0, 2, v16
	s_add_u32 s0, s42, s0
	v_and_b32_e32 v0, 0xfc, v0
	s_addc_u32 s1, s43, s1
	v_lshlrev_b32_e32 v194, 2, v0
	global_load_dwordx4 v[0:3], v194, s[0:1]
	global_load_dwordx4 v[4:7], v194, s[0:1] offset:1024
	global_load_dwordx4 v[8:11], v194, s[0:1] offset:2048
	global_load_dwordx4 v[12:15], v194, s[0:1] offset:3072
	v_readfirstlane_b32 s0, v16
	s_ashr_i32 s0, s0, 6
	v_readlane_b32 s1, v252, 50
	s_add_i32 s6, s0, s1
	s_cmpk_gt_i32 s6, 0x7fff
	v_and_b32_e32 v72, 63, v16
	s_cbranch_scc1 .LBB0_1002
	s_ashr_i32 s7, s6, 31
	s_lshl_b64 s[8:9], s[6:7], 12
	s_add_u32 s8, s82, s8
	s_addc_u32 s9, s83, s9
	global_load_dwordx4 v[44:47], v194, s[8:9] nt
	global_load_dwordx4 v[40:43], v194, s[8:9] offset:1024 nt
	global_load_dwordx4 v[36:39], v194, s[8:9] offset:2048 nt
	global_load_dwordx4 v[16:19], v194, s[8:9] offset:3072 nt
	v_readlane_b32 s8, v255, 21
	v_readlane_b32 s9, v255, 22
	s_add_u32 s5, s8, 0x6000
	v_readlane_b32 s1, v255, 4
	s_addc_u32 s8, s9, 0
	s_add_i32 s0, s1, s0
	s_ashr_i32 s1, s0, 31
	s_lshl_b64 s[10:11], s[6:7], 11
	s_lshl_b64 s[0:1], s[0:1], 12
	v_lshl_or_b32 v64, v72, 3, s10
	v_mov_b32_e32 v65, s11
	v_lshl_or_b32 v66, v72, 4, s0
	v_mov_b32_e32 v67, s1
	s_mov_b32 s9, s6
	s_waitcnt vmcnt(0)
	v_mov_b32_e32 v68, v16
	v_mov_b32_e32 v70, v17
	v_mov_b32_e32 v69, v18
	v_mov_b32_e32 v71, v19
	s_branch .LBB0_1000
